# topk candidate stage: 50-candidate insertion network replaced by merges of the candidates' sorted chains (half-cleaner + 16-wide bitonic merge), 1500 -> 567 VALU; on top of v049
# speedup vs baseline: 1.0051x; 1.0051x over previous
.Ltk_merge:
	s_mov_b64 s[40:41], exec
	s_mov_b64 exec, s[12:13]
	v_mov_b32_e32 v2, v74
	v_mov_b32_e32 v3, v75
	v_mov_b32_e32 v4, v76
	v_mov_b32_e32 v5, v77
	v_mov_b32_e32 v6, v78
	v_mov_b32_e32 v7, v79
	v_mov_b32_e32 v8, v80
	v_mov_b32_e32 v9, v81
	v_mov_b32_e32 v10, v82
	v_mov_b32_e32 v11, v83
	v_mov_b32_e32 v12, v84
	v_mov_b32_e32 v13, v85
	v_mov_b32_e32 v14, v86
	v_mov_b32_e32 v15, v87
	v_mov_b32_e32 v16, v88
	v_mov_b32_e32 v17, v89
	v_mov_b32_e32 v18, v98
	v_mov_b32_e32 v19, v99
	v_mov_b32_e32 v20, v100
	v_mov_b32_e32 v21, v101
	v_mov_b32_e32 v22, v102
	v_mov_b32_e32 v23, v103
	v_mov_b32_e32 v24, v104
	v_mov_b32_e32 v25, v105
	v_mov_b32_e32 v26, v106
	v_mov_b32_e32 v27, v107
	v_mov_b32_e32 v28, v108
	v_mov_b32_e32 v29, v109
	v_mov_b32_e32 v30, v110
	v_mov_b32_e32 v31, v111
	v_mov_b32_e32 v32, v112
	v_mov_b32_e32 v33, v113
	v_add_u32_e32 v36, 0xffff8000, v36
	s_mov_b64 exec, s[40:41]
	v_and_b32_e32 v34, 63, v119
	v_and_b32_e32 v30, 0xffffff80, v30
	v_and_b32_e32 v31, 0xffffff80, v31
	v_and_b32_e32 v32, 0xffffff80, v32
	v_and_b32_e32 v33, 0xffffff80, v33
	v_and_b32_e32 v26, 0xffffff80, v26
	v_and_b32_e32 v27, 0xffffff80, v27
	v_and_b32_e32 v28, 0xffffff80, v28
	v_and_b32_e32 v29, 0xffffff80, v29
	v_and_b32_e32 v22, 0xffffff80, v22
	v_and_b32_e32 v23, 0xffffff80, v23
	v_and_b32_e32 v24, 0xffffff80, v24
	v_and_b32_e32 v25, 0xffffff80, v25
	v_and_b32_e32 v18, 0xffffff80, v18
	v_and_b32_e32 v19, 0xffffff80, v19
	v_and_b32_e32 v20, 0xffffff80, v20
	v_and_b32_e32 v21, 0xffffff80, v21
	v_and_b32_e32 v2, 0xffffff80, v2
	v_and_b32_e32 v3, 0xffffff80, v3
	v_and_b32_e32 v4, 0xffffff80, v4
	v_and_b32_e32 v5, 0xffffff80, v5
	v_and_b32_e32 v14, 0xffffff80, v14
	v_and_b32_e32 v15, 0xffffff80, v15
	v_and_b32_e32 v16, 0xffffff80, v16
	v_and_b32_e32 v17, 0xffffff80, v17
	v_and_b32_e32 v10, 0xffffff80, v10
	v_and_b32_e32 v11, 0xffffff80, v11
	v_and_b32_e32 v12, 0xffffff80, v12
	v_and_b32_e32 v13, 0xffffff80, v13
	v_and_b32_e32 v6, 0xffffff80, v6
	v_and_b32_e32 v7, 0xffffff80, v7
	v_and_b32_e32 v8, 0xffffff80, v8
	v_and_b32_e32 v9, 0xffffff80, v9
	v_add_f32_e32 v35, v30, v2
	v_and_or_b32 v35, v35, s78, 0
	v_add_f32_e32 v42, v30, v3
	v_and_or_b32 v42, v42, s78, 1
	v_add_f32_e32 v43, v30, v4
	v_and_or_b32 v43, v43, s78, 2
	v_add_f32_e32 v44, v30, v5
	v_and_or_b32 v44, v44, s78, 3
	v_add_f32_e32 v45, v30, v14
	v_and_or_b32 v45, v45, s78, 4
	v_add_f32_e32 v46, v30, v15
	v_and_or_b32 v46, v46, s78, 5
	v_add_f32_e32 v47, v30, v16
	v_and_or_b32 v47, v47, s78, 6
	v_add_f32_e32 v48, v30, v17
	v_and_or_b32 v48, v48, s78, 7
	v_add_f32_e32 v49, v30, v10
	v_and_or_b32 v49, v49, s78, 8
	v_add_f32_e32 v50, v30, v11
	v_and_or_b32 v50, v50, s78, 9
	v_add_f32_e32 v51, v30, v12
	v_and_or_b32 v51, v51, s78, 10
	v_add_f32_e32 v52, v30, v13
	v_and_or_b32 v52, v52, s78, 11
	v_add_f32_e32 v53, v30, v6
	v_and_or_b32 v53, v53, s78, 12
	v_add_f32_e32 v54, v30, v7
	v_and_or_b32 v54, v54, s78, 13
	v_add_f32_e32 v55, v30, v8
	v_and_or_b32 v55, v55, s78, 14
	v_add_f32_e32 v56, v30, v9
	v_and_or_b32 v56, v56, s78, 15
	v_add_f32_e32 v57, v31, v2
	v_and_or_b32 v57, v57, s78, 16
	v_add_f32_e32 v58, v31, v3
	v_and_or_b32 v58, v58, s78, 17
	v_add_f32_e32 v59, v31, v4
	v_and_or_b32 v59, v59, s78, 18
	v_add_f32_e32 v60, v31, v5
	v_and_or_b32 v60, v60, s78, 19
	v_add_f32_e32 v61, v31, v14
	v_and_or_b32 v61, v61, s78, 20
	v_add_f32_e32 v154, v31, v15
	v_and_or_b32 v154, v154, s78, 21
	v_add_f32_e32 v205, v31, v16
	v_and_or_b32 v205, v205, s78, 22
	v_add_f32_e32 v206, v31, v17
	v_and_or_b32 v206, v206, s78, 23
	v_max_f32_e32 v56, v56, v57
	v_max_f32_e32 v55, v55, v58
	v_max_f32_e32 v54, v54, v59
	v_max_f32_e32 v53, v53, v60
	v_max_f32_e32 v52, v52, v61
	v_max_f32_e32 v51, v51, v154
	v_max_f32_e32 v50, v50, v205
	v_max_f32_e32 v49, v49, v206
	v_max_f32_e32 v207, v35, v49
	v_min_f32_e32 v49, v35, v49
	v_max_f32_e32 v227, v42, v50
	v_min_f32_e32 v50, v42, v50
	v_max_f32_e32 v228, v43, v51
	v_min_f32_e32 v51, v43, v51
	v_max_f32_e32 v229, v44, v52
	v_min_f32_e32 v52, v44, v52
	v_max_f32_e32 v230, v45, v53
	v_min_f32_e32 v53, v45, v53
	v_max_f32_e32 v231, v46, v54
	v_min_f32_e32 v54, v46, v54
	v_max_f32_e32 v232, v47, v55
	v_min_f32_e32 v55, v47, v55
	v_max_f32_e32 v57, v48, v56
	v_min_f32_e32 v56, v48, v56
	v_max_f32_e32 v58, v207, v230
	v_min_f32_e32 v230, v207, v230
	v_max_f32_e32 v59, v227, v231
	v_min_f32_e32 v231, v227, v231
	v_max_f32_e32 v60, v228, v232
	v_min_f32_e32 v232, v228, v232
	v_max_f32_e32 v61, v229, v57
	v_min_f32_e32 v57, v229, v57
	v_max_f32_e32 v154, v49, v53
	v_min_f32_e32 v53, v49, v53
	v_max_f32_e32 v205, v50, v54
	v_min_f32_e32 v54, v50, v54
	v_max_f32_e32 v206, v51, v55
	v_min_f32_e32 v55, v51, v55
	v_max_f32_e32 v35, v52, v56
	v_min_f32_e32 v56, v52, v56
	v_max_f32_e32 v42, v58, v60
	v_min_f32_e32 v60, v58, v60
	v_max_f32_e32 v43, v59, v61
	v_min_f32_e32 v61, v59, v61
	v_max_f32_e32 v44, v230, v232
	v_min_f32_e32 v232, v230, v232
	v_max_f32_e32 v45, v231, v57
	v_min_f32_e32 v57, v231, v57
	v_max_f32_e32 v46, v154, v206
	v_min_f32_e32 v206, v154, v206
	v_max_f32_e32 v47, v205, v35
	v_min_f32_e32 v35, v205, v35
	v_max_f32_e32 v48, v53, v55
	v_min_f32_e32 v55, v53, v55
	v_max_f32_e32 v207, v54, v56
	v_min_f32_e32 v56, v54, v56
	v_max_f32_e32 v227, v42, v43
	v_min_f32_e32 v43, v42, v43
	v_max_f32_e32 v228, v60, v61
	v_min_f32_e32 v61, v60, v61
	v_max_f32_e32 v229, v44, v45
	v_min_f32_e32 v45, v44, v45
	v_max_f32_e32 v49, v232, v57
	v_min_f32_e32 v57, v232, v57
	v_max_f32_e32 v50, v46, v47
	v_min_f32_e32 v47, v46, v47
	v_max_f32_e32 v51, v206, v35
	v_min_f32_e32 v35, v206, v35
	v_max_f32_e32 v52, v48, v207
	v_min_f32_e32 v207, v48, v207
	v_max_f32_e32 v58, v55, v56
	v_min_f32_e32 v56, v55, v56
	v_add_f32_e32 v59, v32, v2
	v_and_or_b32 v59, v59, s78, 32
	v_add_f32_e32 v230, v32, v3
	v_and_or_b32 v230, v230, s78, 33
	v_add_f32_e32 v231, v32, v4
	v_and_or_b32 v231, v231, s78, 34
	v_add_f32_e32 v154, v32, v5
	v_and_or_b32 v154, v154, s78, 35
	v_add_f32_e32 v205, v32, v14
	v_and_or_b32 v205, v205, s78, 36
	v_max_f32_e32 v56, v56, v59
	v_max_f32_e32 v58, v58, v230
	v_max_f32_e32 v207, v207, v231
	v_max_f32_e32 v52, v52, v154
	v_max_f32_e32 v35, v35, v205
	v_max_f32_e32 v53, v227, v50
	v_min_f32_e32 v50, v227, v50
	v_max_f32_e32 v54, v43, v47
	v_min_f32_e32 v47, v43, v47
	v_max_f32_e32 v42, v228, v51
	v_min_f32_e32 v51, v228, v51
	v_max_f32_e32 v60, v61, v35
	v_min_f32_e32 v35, v61, v35
	v_max_f32_e32 v44, v229, v52
	v_min_f32_e32 v52, v229, v52
	v_max_f32_e32 v232, v45, v207
	v_min_f32_e32 v207, v45, v207
	v_max_f32_e32 v46, v49, v58
	v_min_f32_e32 v58, v49, v58
	v_max_f32_e32 v206, v57, v56
	v_min_f32_e32 v56, v57, v56
	v_max_f32_e32 v48, v53, v44
	v_min_f32_e32 v44, v53, v44
	v_max_f32_e32 v55, v54, v232
	v_min_f32_e32 v232, v54, v232
	v_max_f32_e32 v59, v42, v46
	v_min_f32_e32 v46, v42, v46
	v_max_f32_e32 v230, v60, v206
	v_min_f32_e32 v206, v60, v206
	v_max_f32_e32 v231, v50, v52
	v_min_f32_e32 v52, v50, v52
	v_max_f32_e32 v154, v47, v207
	v_min_f32_e32 v207, v47, v207
	v_max_f32_e32 v205, v51, v58
	v_min_f32_e32 v58, v51, v58
	v_max_f32_e32 v227, v35, v56
	v_min_f32_e32 v56, v35, v56
	v_max_f32_e32 v43, v48, v59
	v_min_f32_e32 v59, v48, v59
	v_max_f32_e32 v228, v55, v230
	v_min_f32_e32 v230, v55, v230
	v_max_f32_e32 v61, v44, v46
	v_min_f32_e32 v46, v44, v46
	v_max_f32_e32 v229, v232, v206
	v_min_f32_e32 v206, v232, v206
	v_max_f32_e32 v45, v231, v205
	v_min_f32_e32 v205, v231, v205
	v_max_f32_e32 v49, v154, v227
	v_min_f32_e32 v227, v154, v227
	v_max_f32_e32 v57, v52, v58
	v_min_f32_e32 v58, v52, v58
	v_max_f32_e32 v53, v207, v56
	v_min_f32_e32 v56, v207, v56
	v_max_f32_e32 v54, v43, v228
	v_min_f32_e32 v228, v43, v228
	v_max_f32_e32 v42, v59, v230
	v_min_f32_e32 v230, v59, v230
	v_max_f32_e32 v60, v61, v229
	v_min_f32_e32 v229, v61, v229
	v_max_f32_e32 v50, v46, v206
	v_min_f32_e32 v206, v46, v206
	v_max_f32_e32 v47, v45, v49
	v_min_f32_e32 v49, v45, v49
	v_max_f32_e32 v51, v205, v227
	v_min_f32_e32 v227, v205, v227
	v_max_f32_e32 v35, v57, v53
	v_min_f32_e32 v53, v57, v53
	v_max_f32_e32 v48, v58, v56
	v_min_f32_e32 v56, v58, v56
	v_add_f32_e32 v55, v33, v2
	v_and_or_b32 v55, v55, s78, 48
	v_add_f32_e32 v44, v33, v3
	v_and_or_b32 v44, v44, s78, 49
	v_add_f32_e32 v232, v33, v4
	v_and_or_b32 v232, v232, s78, 50
	v_add_f32_e32 v231, v33, v5
	v_and_or_b32 v231, v231, s78, 51
	v_max_f32_e32 v56, v56, v55
	v_max_f32_e32 v48, v48, v44
	v_max_f32_e32 v53, v53, v232
	v_max_f32_e32 v35, v35, v231
	v_max_f32_e32 v154, v54, v47
	v_min_f32_e32 v47, v54, v47
	v_max_f32_e32 v52, v228, v49
	v_min_f32_e32 v49, v228, v49
	v_max_f32_e32 v207, v42, v51
	v_min_f32_e32 v51, v42, v51
	v_max_f32_e32 v43, v230, v227
	v_min_f32_e32 v227, v230, v227
	v_max_f32_e32 v59, v60, v35
	v_min_f32_e32 v35, v60, v35
	v_max_f32_e32 v61, v229, v53
	v_min_f32_e32 v53, v229, v53
	v_max_f32_e32 v46, v50, v48
	v_min_f32_e32 v48, v50, v48
	v_max_f32_e32 v45, v206, v56
	v_min_f32_e32 v56, v206, v56
	v_max_f32_e32 v205, v154, v59
	v_min_f32_e32 v59, v154, v59
	v_max_f32_e32 v57, v52, v61
	v_min_f32_e32 v61, v52, v61
	v_max_f32_e32 v58, v207, v46
	v_min_f32_e32 v46, v207, v46
	v_max_f32_e32 v55, v43, v45
	v_min_f32_e32 v45, v43, v45
	v_max_f32_e32 v44, v47, v35
	v_min_f32_e32 v35, v47, v35
	v_max_f32_e32 v232, v49, v53
	v_min_f32_e32 v53, v49, v53
	v_max_f32_e32 v231, v51, v48
	v_min_f32_e32 v48, v51, v48
	v_max_f32_e32 v54, v227, v56
	v_min_f32_e32 v56, v227, v56
	v_max_f32_e32 v228, v205, v58
	v_min_f32_e32 v58, v205, v58
	v_max_f32_e32 v42, v57, v55
	v_min_f32_e32 v55, v57, v55
	v_max_f32_e32 v230, v59, v46
	v_min_f32_e32 v46, v59, v46
	v_max_f32_e32 v60, v61, v45
	v_min_f32_e32 v45, v61, v45
	v_max_f32_e32 v229, v44, v231
	v_min_f32_e32 v231, v44, v231
	v_max_f32_e32 v50, v232, v54
	v_min_f32_e32 v54, v232, v54
	v_max_f32_e32 v206, v35, v48
	v_min_f32_e32 v48, v35, v48
	v_max_f32_e32 v154, v53, v56
	v_min_f32_e32 v56, v53, v56
	v_max_f32_e32 v52, v228, v42
	v_min_f32_e32 v42, v228, v42
	v_max_f32_e32 v207, v58, v55
	v_min_f32_e32 v55, v58, v55
	v_max_f32_e32 v43, v230, v60
	v_min_f32_e32 v60, v230, v60
	v_max_f32_e32 v47, v46, v45
	v_min_f32_e32 v45, v46, v45
	v_max_f32_e32 v49, v229, v50
	v_min_f32_e32 v50, v229, v50
	v_max_f32_e32 v51, v231, v54
	v_min_f32_e32 v54, v231, v54
	v_max_f32_e32 v227, v206, v154
	v_min_f32_e32 v154, v206, v154
	v_max_f32_e32 v205, v48, v56
	v_min_f32_e32 v56, v48, v56
	v_add_f32_e32 v57, v26, v2
	v_and_or_b32 v57, v57, s78, 64
	v_add_f32_e32 v59, v26, v3
	v_and_b32_e32 v59, s78, v59
	v_or_b32_e32 v59, 0x41, v59
	v_add_f32_e32 v61, v26, v4
	v_and_b32_e32 v61, s78, v61
	v_or_b32_e32 v61, 0x42, v61
	v_max_f32_e32 v56, v56, v57
	v_max_f32_e32 v205, v205, v59
	v_max_f32_e32 v154, v154, v61
	v_max_f32_e32 v44, v52, v49
	v_min_f32_e32 v49, v52, v49
	v_max_f32_e32 v232, v42, v50
	v_min_f32_e32 v50, v42, v50
	v_max_f32_e32 v35, v207, v51
	v_min_f32_e32 v51, v207, v51
	v_max_f32_e32 v53, v55, v54
	v_min_f32_e32 v54, v55, v54
	v_max_f32_e32 v228, v43, v227
	v_min_f32_e32 v227, v43, v227
	v_max_f32_e32 v58, v60, v154
	v_min_f32_e32 v154, v60, v154
	v_max_f32_e32 v230, v47, v205
	v_min_f32_e32 v205, v47, v205
	v_max_f32_e32 v46, v45, v56
	v_min_f32_e32 v56, v45, v56
	v_max_f32_e32 v229, v44, v228
	v_min_f32_e32 v228, v44, v228
	v_max_f32_e32 v231, v232, v58
	v_min_f32_e32 v58, v232, v58
	v_max_f32_e32 v206, v35, v230
	v_min_f32_e32 v230, v35, v230
	v_max_f32_e32 v48, v53, v46
	v_min_f32_e32 v46, v53, v46
	v_max_f32_e32 v57, v49, v227
	v_min_f32_e32 v227, v49, v227
	v_max_f32_e32 v59, v50, v154
	v_min_f32_e32 v154, v50, v154
	v_max_f32_e32 v61, v51, v205
	v_min_f32_e32 v205, v51, v205
	v_max_f32_e32 v52, v54, v56
	v_min_f32_e32 v56, v54, v56
	v_max_f32_e32 v42, v229, v206
	v_min_f32_e32 v206, v229, v206
	v_max_f32_e32 v207, v231, v48
	v_min_f32_e32 v48, v231, v48
	v_max_f32_e32 v55, v228, v230
	v_min_f32_e32 v230, v228, v230
	v_max_f32_e32 v43, v58, v46
	v_min_f32_e32 v46, v58, v46
	v_max_f32_e32 v60, v57, v61
	v_min_f32_e32 v61, v57, v61
	v_max_f32_e32 v47, v59, v52
	v_min_f32_e32 v52, v59, v52
	v_max_f32_e32 v45, v227, v205
	v_min_f32_e32 v205, v227, v205
	v_max_f32_e32 v44, v154, v56
	v_min_f32_e32 v56, v154, v56
	v_max_f32_e32 v232, v42, v207
	v_min_f32_e32 v207, v42, v207
	v_max_f32_e32 v35, v206, v48
	v_min_f32_e32 v48, v206, v48
	v_max_f32_e32 v53, v55, v43
	v_min_f32_e32 v43, v55, v43
	v_max_f32_e32 v49, v230, v46
	v_min_f32_e32 v46, v230, v46
	v_max_f32_e32 v50, v60, v47
	v_min_f32_e32 v47, v60, v47
	v_max_f32_e32 v51, v61, v52
	v_min_f32_e32 v52, v61, v52
	v_max_f32_e32 v54, v45, v44
	v_min_f32_e32 v44, v45, v44
	v_max_f32_e32 v229, v205, v56
	v_min_f32_e32 v56, v205, v56
	v_add_f32_e32 v231, v27, v2
	v_and_b32_e32 v231, s78, v231
	v_or_b32_e32 v231, 0x50, v231
	v_add_f32_e32 v228, v28, v2
	v_and_b32_e32 v228, s78, v228
	v_or_b32_e32 v228, 0x60, v228
	v_add_f32_e32 v58, v29, v2
	v_and_b32_e32 v58, s78, v58
	v_or_b32_e32 v58, 0x70, v58
	v_add_f32_e32 v57, v22, v2
	v_and_b32_e32 v57, s78, v57
	v_or_b32_e32 v57, 0x80, v57
	v_add_f32_e32 v59, v23, v2
	v_and_b32_e32 v59, s78, v59
	v_or_b32_e32 v59, 0x90, v59
	v_add_f32_e32 v227, v24, v2
	v_and_b32_e32 v227, s78, v227
	v_or_b32_e32 v227, 0xa0, v227
	v_add_f32_e32 v154, v25, v2
	v_and_b32_e32 v154, s78, v154
	v_or_b32_e32 v154, 0xb0, v154
	v_add_f32_e32 v42, v18, v2
	v_and_b32_e32 v42, s78, v42
	v_or_b32_e32 v42, 0xc0, v42
	v_add_f32_e32 v206, v19, v2
	v_and_b32_e32 v206, s78, v206
	v_or_b32_e32 v206, 0xd0, v206
	v_add_f32_e32 v55, v20, v2
	v_and_b32_e32 v55, s78, v55
	v_or_b32_e32 v55, 0xe0, v55
	v_add_f32_e32 v230, v21, v2
	v_and_b32_e32 v230, s78, v230
	v_or_b32_e32 v230, 0xf0, v230
	v_max_f32_e32 v56, v56, v231
	v_max_f32_e32 v229, v229, v228
	v_max_f32_e32 v44, v44, v58
	v_max_f32_e32 v54, v54, v57
	v_max_f32_e32 v52, v52, v59
	v_max_f32_e32 v51, v51, v227
	v_max_f32_e32 v47, v47, v154
	v_max_f32_e32 v50, v50, v42
	v_max_f32_e32 v46, v46, v206
	v_max_f32_e32 v49, v49, v55
	v_max_f32_e32 v43, v43, v230
	v_max_f32_e32 v60, v232, v50
	v_min_f32_e32 v50, v232, v50
	v_max_f32_e32 v61, v207, v47
	v_min_f32_e32 v47, v207, v47
	v_max_f32_e32 v45, v35, v51
	v_min_f32_e32 v51, v35, v51
	v_max_f32_e32 v205, v48, v52
	v_min_f32_e32 v52, v48, v52
	v_max_f32_e32 v231, v53, v54
	v_min_f32_e32 v54, v53, v54
	v_max_f32_e32 v228, v43, v44
	v_min_f32_e32 v44, v43, v44
	v_max_f32_e32 v58, v49, v229
	v_min_f32_e32 v229, v49, v229
	v_max_f32_e32 v57, v46, v56
	v_min_f32_e32 v56, v46, v56
	v_max_f32_e32 v59, v60, v231
	v_min_f32_e32 v231, v60, v231
	v_max_f32_e32 v227, v61, v228
	v_min_f32_e32 v228, v61, v228
	v_max_f32_e32 v154, v45, v58
	v_min_f32_e32 v58, v45, v58
	v_max_f32_e32 v42, v205, v57
	v_min_f32_e32 v57, v205, v57
	v_max_f32_e32 v206, v50, v54
	v_min_f32_e32 v54, v50, v54
	v_max_f32_e32 v55, v47, v44
	v_min_f32_e32 v44, v47, v44
	v_max_f32_e32 v230, v51, v229
	v_min_f32_e32 v229, v51, v229
	v_max_f32_e32 v232, v52, v56
	v_min_f32_e32 v56, v52, v56
	v_max_f32_e32 v207, v59, v154
	v_min_f32_e32 v154, v59, v154
	v_max_f32_e32 v35, v227, v42
	v_min_f32_e32 v42, v227, v42
	v_max_f32_e32 v48, v231, v58
	v_min_f32_e32 v58, v231, v58
	v_max_f32_e32 v53, v228, v57
	v_min_f32_e32 v57, v228, v57
	v_max_f32_e32 v43, v206, v230
	v_min_f32_e32 v230, v206, v230
	v_max_f32_e32 v49, v55, v232
	v_min_f32_e32 v232, v55, v232
	v_max_f32_e32 v46, v54, v229
	v_min_f32_e32 v229, v54, v229
	v_max_f32_e32 v60, v44, v56
	v_min_f32_e32 v56, v44, v56
	v_max_f32_e32 v61, v207, v35
	v_min_f32_e32 v35, v207, v35
	v_max_f32_e32 v45, v154, v42
	v_min_f32_e32 v42, v154, v42
	v_max_f32_e32 v205, v48, v53
	v_min_f32_e32 v53, v48, v53
	v_max_f32_e32 v50, v58, v57
	v_min_f32_e32 v57, v58, v57
	v_max_f32_e32 v47, v43, v49
	v_min_f32_e32 v49, v43, v49
	v_max_f32_e32 v51, v230, v232
	v_min_f32_e32 v232, v230, v232
	v_max_f32_e32 v52, v46, v60
	v_min_f32_e32 v60, v46, v60
	v_max_f32_e32 v59, v229, v56
	v_min_f32_e32 v56, v229, v56
	v_add_f32_e32 v227, v27, v3
	v_and_b32_e32 v227, s78, v227
	v_or_b32_e32 v227, 0x51, v227
	v_add_f32_e32 v231, v28, v3
	v_and_b32_e32 v231, s78, v231
	v_or_b32_e32 v231, 0x61, v231
	v_add_f32_e32 v228, v29, v3
	v_and_b32_e32 v228, s78, v228
	v_or_b32_e32 v228, 0x71, v228
	v_max_f32_e32 v56, v56, v227
	v_max_f32_e32 v59, v59, v231
	v_max_f32_e32 v60, v60, v228
	v_max_f32_e32 v206, v61, v47
	v_min_f32_e32 v47, v61, v47
	v_max_f32_e32 v55, v35, v49
	v_min_f32_e32 v49, v35, v49
	v_max_f32_e32 v54, v45, v51
	v_min_f32_e32 v51, v45, v51
	v_max_f32_e32 v44, v42, v232
	v_min_f32_e32 v232, v42, v232
	v_max_f32_e32 v207, v205, v52
	v_min_f32_e32 v52, v205, v52
	v_max_f32_e32 v154, v53, v60
	v_min_f32_e32 v60, v53, v60
	v_max_f32_e32 v48, v50, v59
	v_min_f32_e32 v59, v50, v59
	v_max_f32_e32 v58, v57, v56
	v_min_f32_e32 v56, v57, v56
	v_max_f32_e32 v43, v206, v207
	v_min_f32_e32 v207, v206, v207
	v_max_f32_e32 v230, v55, v154
	v_min_f32_e32 v154, v55, v154
	v_max_f32_e32 v46, v54, v48
	v_min_f32_e32 v48, v54, v48
	v_max_f32_e32 v229, v44, v58
	v_min_f32_e32 v58, v44, v58
	v_max_f32_e32 v227, v47, v52
	v_min_f32_e32 v52, v47, v52
	v_max_f32_e32 v231, v49, v60
	v_min_f32_e32 v60, v49, v60
	v_max_f32_e32 v228, v51, v59
	v_min_f32_e32 v59, v51, v59
	v_max_f32_e32 v61, v232, v56
	v_min_f32_e32 v56, v232, v56
	v_max_f32_e32 v35, v43, v46
	v_min_f32_e32 v46, v43, v46
	v_max_f32_e32 v45, v230, v229
	v_min_f32_e32 v229, v230, v229
	v_max_f32_e32 v42, v207, v48
	v_min_f32_e32 v48, v207, v48
	v_max_f32_e32 v205, v154, v58
	v_min_f32_e32 v58, v154, v58
	v_max_f32_e32 v53, v227, v228
	v_min_f32_e32 v228, v227, v228
	v_max_f32_e32 v50, v231, v61
	v_min_f32_e32 v61, v231, v61
	v_max_f32_e32 v57, v52, v59
	v_min_f32_e32 v59, v52, v59
	v_max_f32_e32 v206, v60, v56
	v_min_f32_e32 v56, v60, v56
	v_max_f32_e32 v41, v35, v45
	v_min_f32_e32 v40, v35, v45
	v_max_f32_e32 v39, v46, v229
	v_min_f32_e32 v38, v46, v229
	v_max_f32_e32 v37, v42, v205
	v_min_f32_e32 v33, v42, v205
	v_max_f32_e32 v32, v48, v58
	v_min_f32_e32 v31, v48, v58
	v_max_f32_e32 v30, v53, v50
	v_min_f32_e32 v29, v53, v50
	v_max_f32_e32 v28, v228, v61
	v_min_f32_e32 v27, v228, v61
	v_max_f32_e32 v26, v57, v206
	v_min_f32_e32 v25, v57, v206
	v_max_f32_e32 v24, v59, v56
	v_min_f32_e32 v19, v59, v56
	v_and_b32_e32 v17, 0xffffff00, v41
	v_sub_f32_e32 v2, v17, v17
	v_mul_f32_e32 v6, 0x3fb8aa3b, v2
	v_fma_f32 v7, v2, s79, -v6
	v_rndne_f32_e32 v22, v6
	v_fmac_f32_e32 v7, 0x32a5705f, v2
	v_sub_f32_e32 v6, v6, v22
	v_add_f32_e32 v6, v6, v7
	v_exp_f32_e32 v6, v6
	v_cvt_i32_f32_e32 v7, v22
	v_and_b32_e32 v3, 0xffffff00, v40
	v_cmp_ngt_f32_e32 vcc, s80, v2
	v_sub_f32_e32 v3, v3, v17
	v_ldexp_f32 v6, v6, v7
	v_cndmask_b32_e32 v6, 0, v6, vcc
	v_cmp_nlt_f32_e32 vcc, s81, v2
	v_and_b32_e32 v4, 0xffffff00, v39
	v_sub_f32_e32 v4, v4, v17
	v_cndmask_b32_e32 v2, v217, v6, vcc
	v_mul_f32_e32 v6, 0x3fb8aa3b, v3
	v_fma_f32 v7, v3, s79, -v6
	v_rndne_f32_e32 v22, v6
	v_fmac_f32_e32 v7, 0x32a5705f, v3
	v_sub_f32_e32 v6, v6, v22
	v_add_f32_e32 v6, v6, v7
	v_exp_f32_e32 v6, v6
	v_cvt_i32_f32_e32 v7, v22
	v_cmp_ngt_f32_e32 vcc, s80, v3
	v_and_b32_e32 v5, 0xffffff00, v38
	v_sub_f32_e32 v5, v5, v17
	v_ldexp_f32 v6, v6, v7
	v_cndmask_b32_e32 v6, 0, v6, vcc
	v_cmp_nlt_f32_e32 vcc, s81, v3
	v_and_b32_e32 v8, 0xffffff00, v37
	v_and_b32_e32 v9, 0xffffff00, v33
	v_cndmask_b32_e32 v3, v217, v6, vcc
	v_mul_f32_e32 v6, 0x3fb8aa3b, v4
	v_fma_f32 v22, v4, s79, -v6
	v_rndne_f32_e32 v23, v6
	v_fmac_f32_e32 v22, 0x32a5705f, v4
	v_sub_f32_e32 v6, v6, v23
	v_add_f32_e32 v6, v6, v22
	v_exp_f32_e32 v6, v6
	v_cvt_i32_f32_e32 v22, v23
	v_cmp_ngt_f32_e32 vcc, s80, v4
	v_add_f32_e32 v7, v2, v3
	v_and_b32_e32 v10, 0xffffff00, v32
	v_ldexp_f32 v6, v6, v22
	v_cndmask_b32_e32 v6, 0, v6, vcc
	v_cmp_nlt_f32_e32 vcc, s81, v4
	v_and_b32_e32 v11, 0xffffff00, v31
	v_and_b32_e32 v12, 0xffffff00, v30
	v_cndmask_b32_e32 v6, v217, v6, vcc
	v_add_f32_e32 v4, v7, v6
	v_mul_f32_e32 v7, 0x3fb8aa3b, v5
	v_fma_f32 v22, v5, s79, -v7
	v_rndne_f32_e32 v23, v7
	v_fmac_f32_e32 v22, 0x32a5705f, v5
	v_sub_f32_e32 v7, v7, v23
	v_add_f32_e32 v7, v7, v22
	v_exp_f32_e32 v7, v7
	v_cvt_i32_f32_e32 v22, v23
	v_cmp_ngt_f32_e32 vcc, s80, v5
	v_and_b32_e32 v14, 0xffffff00, v29
	v_and_b32_e32 v15, 0xffffff00, v28
	v_ldexp_f32 v7, v7, v22
	v_cndmask_b32_e32 v7, 0, v7, vcc
	v_cmp_nlt_f32_e32 vcc, s81, v5
	v_and_b32_e32 v20, 0xffffff00, v27
	v_and_b32_e32 v21, 0xffffff00, v26
	v_cndmask_b32_e32 v7, v217, v7, vcc
	v_add_f32_e32 v5, v4, v7
	v_sub_f32_e32 v4, v8, v17
	v_mul_f32_e32 v8, 0x3fb8aa3b, v4
	v_fma_f32 v22, v4, s79, -v8
	v_rndne_f32_e32 v23, v8
	v_fmac_f32_e32 v22, 0x32a5705f, v4
	v_sub_f32_e32 v8, v8, v23
	v_add_f32_e32 v8, v8, v22
	v_exp_f32_e32 v8, v8
	v_cvt_i32_f32_e32 v22, v23
	v_cmp_ngt_f32_e32 vcc, s80, v4
	v_and_b32_e32 v13, 0xffffff00, v25
	v_sub_f32_e32 v13, v13, v17
	v_ldexp_f32 v8, v8, v22
	v_cndmask_b32_e32 v8, 0, v8, vcc
	v_cmp_nlt_f32_e32 vcc, s81, v4
	v_and_b32_e32 v16, 0xffffff00, v24
	v_sub_f32_e32 v16, v16, v17
	v_cndmask_b32_e32 v4, v217, v8, vcc
	v_add_f32_e32 v8, v5, v4
	v_sub_f32_e32 v5, v9, v17
	v_mul_f32_e32 v9, 0x3fb8aa3b, v5
	v_fma_f32 v22, v5, s79, -v9
	v_rndne_f32_e32 v23, v9
	v_fmac_f32_e32 v22, 0x32a5705f, v5
	v_sub_f32_e32 v9, v9, v23
	v_add_f32_e32 v9, v9, v22
	v_exp_f32_e32 v9, v9
	v_cvt_i32_f32_e32 v22, v23
	v_cmp_ngt_f32_e32 vcc, s80, v5
	v_and_b32_e32 v18, 0xffffff00, v19
	s_mov_b32 s10, s42
	v_ldexp_f32 v9, v9, v22
	v_cndmask_b32_e32 v9, 0, v9, vcc
	v_cmp_nlt_f32_e32 vcc, s81, v5
	v_or_b32_e32 v34, s10, v34
	v_lshrrev_b32_e32 v42, 2, v39
	v_cndmask_b32_e32 v5, v217, v9, vcc
	v_sub_f32_e32 v9, v10, v17
	v_mul_f32_e32 v10, 0x3fb8aa3b, v9
	v_fma_f32 v22, v9, s79, -v10
	v_rndne_f32_e32 v23, v10
	v_fmac_f32_e32 v22, 0x32a5705f, v9
	v_sub_f32_e32 v10, v10, v23
	v_add_f32_e32 v10, v10, v22
	v_exp_f32_e32 v10, v10
	v_cvt_i32_f32_e32 v22, v23
	v_cmp_ngt_f32_e32 vcc, s80, v9
	v_add_f32_e32 v8, v8, v5
	v_and_b32_e32 v39, 15, v39
	v_ldexp_f32 v10, v10, v22
	v_cndmask_b32_e32 v10, 0, v10, vcc
	v_cmp_nlt_f32_e32 vcc, s81, v9
	v_sub_f32_e32 v9, v11, v17
	v_mul_f32_e32 v11, 0x3fb8aa3b, v9
	v_fma_f32 v22, v9, s79, -v11
	v_rndne_f32_e32 v23, v11
	v_fmac_f32_e32 v22, 0x32a5705f, v9
	v_sub_f32_e32 v11, v11, v23
	v_add_f32_e32 v11, v11, v22
	v_exp_f32_e32 v11, v11
	v_cvt_i32_f32_e32 v22, v23
	v_cndmask_b32_e32 v10, v217, v10, vcc
	v_cmp_ngt_f32_e32 vcc, s80, v9
	v_add_f32_e32 v8, v8, v10
	v_ldexp_f32 v11, v11, v22
	v_cndmask_b32_e32 v11, 0, v11, vcc
	v_cmp_nlt_f32_e32 vcc, s81, v9
	v_lshl_add_u32 v39, v39, 2, v36
	ds_read_b32 v43, v39 offset:64
	v_cndmask_b32_e32 v11, v217, v11, vcc
	v_add_f32_e32 v9, v8, v11
	v_sub_f32_e32 v8, v12, v17
	v_mul_f32_e32 v12, 0x3fb8aa3b, v8
	v_fma_f32 v22, v8, s79, -v12
	v_rndne_f32_e32 v23, v12
	v_fmac_f32_e32 v22, 0x32a5705f, v8
	v_sub_f32_e32 v12, v12, v23
	v_add_f32_e32 v12, v12, v22
	v_exp_f32_e32 v12, v12
	v_cvt_i32_f32_e32 v22, v23
	v_cmp_ngt_f32_e32 vcc, s80, v8
	v_lshrrev_b32_e32 v39, 2, v38
	v_and_b32_e32 v42, 60, v42
	v_ldexp_f32 v12, v12, v22
	v_cndmask_b32_e32 v12, 0, v12, vcc
	v_cmp_nlt_f32_e32 vcc, s81, v8
	v_and_b32_e32 v39, 60, v39
	v_add_u32_e32 v42, v36, v42
	v_cndmask_b32_e32 v8, v217, v12, vcc
	v_add_f32_e32 v12, v9, v8
	v_sub_f32_e32 v9, v14, v17
	v_mul_f32_e32 v14, 0x3fb8aa3b, v9
	v_fma_f32 v22, v9, s79, -v14
	v_rndne_f32_e32 v23, v14
	v_fmac_f32_e32 v22, 0x32a5705f, v9
	v_sub_f32_e32 v14, v14, v23
	v_add_f32_e32 v14, v14, v22
	v_exp_f32_e32 v14, v14
	v_cvt_i32_f32_e32 v22, v23
	v_cmp_ngt_f32_e32 vcc, s80, v9
	v_add_u32_e32 v39, v36, v39
	v_and_b32_e32 v38, 15, v38
	v_ldexp_f32 v14, v14, v22
	v_cndmask_b32_e32 v14, 0, v14, vcc
	v_cmp_nlt_f32_e32 vcc, s81, v9
	ds_read_b32 v42, v42
	ds_read_b32 v44, v39
	v_cndmask_b32_e32 v9, v217, v14, vcc
	v_sub_f32_e32 v14, v15, v17
	v_mul_f32_e32 v15, 0x3fb8aa3b, v14
	v_fma_f32 v22, v14, s79, -v15
	v_rndne_f32_e32 v23, v15
	v_fmac_f32_e32 v22, 0x32a5705f, v14
	v_sub_f32_e32 v15, v15, v23
	v_add_f32_e32 v15, v15, v22
	v_exp_f32_e32 v15, v15
	v_cvt_i32_f32_e32 v22, v23
	v_cmp_ngt_f32_e32 vcc, s80, v14
	v_add_f32_e32 v12, v12, v9
	v_lshl_add_u32 v38, v38, 2, v36
	v_ldexp_f32 v15, v15, v22
	v_cndmask_b32_e32 v15, 0, v15, vcc
	v_cmp_nlt_f32_e32 vcc, s81, v14
	ds_read_b32 v45, v38 offset:64
	s_nop 0
	v_cndmask_b32_e32 v14, v217, v15, vcc
	v_sub_f32_e32 v15, v20, v17
	v_mul_f32_e32 v20, 0x3fb8aa3b, v15
	v_fma_f32 v22, v15, s79, -v20
	v_rndne_f32_e32 v23, v20
	v_fmac_f32_e32 v22, 0x32a5705f, v15
	v_sub_f32_e32 v20, v20, v23
	v_add_f32_e32 v20, v20, v22
	v_exp_f32_e32 v20, v20
	v_cvt_i32_f32_e32 v22, v23
	v_cmp_ngt_f32_e32 vcc, s80, v15
	v_add_f32_e32 v12, v12, v14
	v_ldexp_f32 v20, v20, v22
	v_cndmask_b32_e32 v20, 0, v20, vcc
	v_cmp_nlt_f32_e32 vcc, s81, v15
	s_nop 1
	v_cndmask_b32_e32 v15, v217, v20, vcc
	v_add_f32_e32 v20, v12, v15
	v_sub_f32_e32 v12, v21, v17
	v_mul_f32_e32 v21, 0x3fb8aa3b, v12
	v_fma_f32 v22, v12, s79, -v21
	v_rndne_f32_e32 v23, v21
	v_fmac_f32_e32 v22, 0x32a5705f, v12
	v_sub_f32_e32 v21, v21, v23
	v_add_f32_e32 v21, v21, v22
	v_exp_f32_e32 v21, v21
	v_cvt_i32_f32_e32 v22, v23
	v_cmp_ngt_f32_e32 vcc, s80, v12
	v_sub_f32_e32 v17, v18, v17
	v_mul_f32_e32 v18, 0x3fb8aa3b, v17
	v_ldexp_f32 v21, v21, v22
	v_cndmask_b32_e32 v21, 0, v21, vcc
	v_cmp_nlt_f32_e32 vcc, s81, v12
	s_nop 1
	v_cndmask_b32_e32 v12, v217, v21, vcc
	v_mul_f32_e32 v21, 0x3fb8aa3b, v13
	v_fma_f32 v22, v13, s79, -v21
	v_rndne_f32_e32 v23, v21
	v_fmac_f32_e32 v22, 0x32a5705f, v13
	v_sub_f32_e32 v21, v21, v23
	v_add_f32_e32 v21, v21, v22
	v_exp_f32_e32 v21, v21
	v_cvt_i32_f32_e32 v22, v23
	v_cmp_ngt_f32_e32 vcc, s80, v13
	v_add_f32_e32 v20, v20, v12
	v_ldexp_f32 v21, v21, v22
	v_cndmask_b32_e32 v21, 0, v21, vcc
	v_cmp_nlt_f32_e32 vcc, s81, v13
	s_nop 1
	v_cndmask_b32_e32 v13, v217, v21, vcc
	v_mul_f32_e32 v21, 0x3fb8aa3b, v16
	v_fma_f32 v22, v16, s79, -v21
	v_rndne_f32_e32 v23, v21
	v_fmac_f32_e32 v22, 0x32a5705f, v16
	v_sub_f32_e32 v21, v21, v23
	v_add_f32_e32 v21, v21, v22
	v_exp_f32_e32 v21, v21
	v_cvt_i32_f32_e32 v22, v23
	v_cmp_ngt_f32_e32 vcc, s80, v16
	v_add_f32_e32 v20, v20, v13
	v_ldexp_f32 v21, v21, v22
	v_cndmask_b32_e32 v21, 0, v21, vcc
	v_cmp_nlt_f32_e32 vcc, s81, v16
	v_rndne_f32_e32 v22, v18
	s_nop 0
	v_cndmask_b32_e32 v16, v217, v21, vcc
	v_fma_f32 v21, v17, s79, -v18
	v_fmac_f32_e32 v21, 0x32a5705f, v17
	v_sub_f32_e32 v18, v18, v22
	v_add_f32_e32 v18, v18, v21
	v_exp_f32_e32 v18, v18
	v_cvt_i32_f32_e32 v21, v22
	v_cmp_ngt_f32_e32 vcc, s80, v17
	v_add_f32_e32 v20, v20, v16
	v_ldexp_f32 v18, v18, v21
	v_cndmask_b32_e32 v18, 0, v18, vcc
	v_cmp_nlt_f32_e32 vcc, s81, v17
	s_nop 1
	v_cndmask_b32_e32 v17, v217, v18, vcc
	v_add_f32_e32 v18, v20, v17
	v_div_scale_f32 v20, s[10:11], v18, v18, 1.0
	v_rcp_f32_e32 v21, v20
	s_nop 0
	v_fma_f32 v22, -v20, v21, 1.0
	v_fmac_f32_e32 v21, v22, v21
	v_div_scale_f32 v22, vcc, 1.0, v18, 1.0
	v_mul_f32_e32 v23, v22, v21
	v_fma_f32 v35, -v20, v23, v22
	v_fmac_f32_e32 v23, v35, v21
	v_fma_f32 v20, -v20, v23, v22
	v_div_fmas_f32 v20, v20, v21, v23
	v_ashrrev_i32_e32 v35, 31, v34
	v_div_fixup_f32 v18, v20, v18, 1.0
	v_lshlrev_b64 v[20:21], 9, v[34:35]
	v_lshrrev_b32_e32 v34, 2, v41
	v_and_b32_e32 v35, 15, v41
	v_lshrrev_b32_e32 v41, 2, v40
	v_and_b32_e32 v41, 60, v41
	v_add_u32_e32 v41, v36, v41
	v_and_b32_e32 v34, 60, v34
	ds_read_b32 v41, v41
	v_add_u32_e32 v34, v36, v34
	v_and_b32_e32 v40, 15, v40
	ds_read_b32 v34, v34
	v_lshl_add_u32 v35, v35, 2, v36
	v_lshl_add_u32 v40, v40, 2, v36
	ds_read_b32 v35, v35 offset:64
	ds_read_b32 v40, v40 offset:64
	s_waitcnt lgkmcnt(3)
	v_lshlrev_b32_e32 v39, 7, v41
	s_waitcnt lgkmcnt(2)
	v_lshlrev_b32_e32 v34, 7, v34
	v_and_b32_e32 v39, 0x3f80, v39
	s_waitcnt lgkmcnt(1)
	v_and_b32_e32 v35, 0x7f, v35
	s_waitcnt lgkmcnt(0)
	v_and_b32_e32 v38, 0x7f, v40
	v_and_b32_e32 v34, 0x3f80, v34
	v_lshlrev_b32_e32 v40, 7, v44
	v_lshlrev_b32_e32 v41, 7, v42
	v_or_b32_e32 v39, v39, v38
	v_or_b32_e32 v38, v34, v35
	v_and_b32_e32 v34, 0x7f, v45
	v_and_b32_e32 v35, 0x7f, v43
	v_and_b32_e32 v40, 0x3f80, v40
	v_and_b32_e32 v42, 0x3f80, v41
	v_lshl_add_u64 v[22:23], s[0:1], 0, v[20:21]
	v_or_b32_e32 v41, v40, v34
	v_or_b32_e32 v40, v42, v35
	global_store_dwordx4 v[22:23], v[38:41], off
	v_lshl_add_u64 v[20:21], s[14:15], 0, v[20:21]
	v_pk_mul_f32 v[4:5], v[4:5], v[18:19] op_sel_hi:[1,0]
	v_pk_mul_f32 v[40:41], v[6:7], v[18:19] op_sel_hi:[1,0]
	v_pk_mul_f32 v[38:39], v[2:3], v[18:19] op_sel_hi:[1,0]
	v_lshrrev_b32_e32 v2, 2, v37
	v_lshrrev_b32_e32 v6, 2, v33
	v_and_b32_e32 v7, 15, v33
	v_lshrrev_b32_e32 v33, 2, v32
	v_and_b32_e32 v32, 15, v32
	v_and_b32_e32 v2, 60, v2
	v_and_b32_e32 v3, 15, v37
	v_and_b32_e32 v6, 60, v6
	v_lshl_add_u32 v32, v32, 2, v36
	v_add_u32_e32 v2, v36, v2
	v_lshl_add_u32 v3, v3, 2, v36
	v_add_u32_e32 v6, v36, v6
	ds_read_b32 v35, v32 offset:64
	v_lshrrev_b32_e32 v32, 2, v31
	ds_read_b32 v2, v2
	ds_read_b32 v3, v3 offset:64
	ds_read_b32 v6, v6
	v_lshl_add_u32 v7, v7, 2, v36
	v_and_b32_e32 v33, 60, v33
	v_and_b32_e32 v32, 60, v32
	ds_read_b32 v7, v7 offset:64
	v_add_u32_e32 v33, v36, v33
	v_add_u32_e32 v32, v36, v32
	v_and_b32_e32 v31, 15, v31
	ds_read_b32 v34, v33
	ds_read_b32 v37, v32
	v_lshl_add_u32 v31, v31, 2, v36
	ds_read_b32 v31, v31 offset:64
	s_waitcnt lgkmcnt(4)
	v_lshlrev_b32_e32 v6, 7, v6
	s_waitcnt lgkmcnt(3)
	v_and_b32_e32 v7, 0x7f, v7
	v_lshlrev_b32_e32 v2, 7, v2
	v_and_b32_e32 v6, 0x3f80, v6
	v_and_b32_e32 v3, 0x7f, v3
	v_and_b32_e32 v2, 0x3f80, v2
	v_or_b32_e32 v33, v6, v7
	s_waitcnt lgkmcnt(1)
	v_lshlrev_b32_e32 v6, 7, v37
	v_lshlrev_b32_e32 v7, 7, v34
	v_or_b32_e32 v32, v2, v3
	s_waitcnt lgkmcnt(0)
	v_and_b32_e32 v2, 0x7f, v31
	v_and_b32_e32 v3, 0x7f, v35
	v_and_b32_e32 v6, 0x3f80, v6
	v_and_b32_e32 v7, 0x3f80, v7
	v_or_b32_e32 v35, v6, v2
	v_or_b32_e32 v34, v7, v3
	v_pk_mul_f32 v[6:7], v[10:11], v[18:19] op_sel_hi:[1,0]
	global_store_dwordx4 v[20:21], v[4:7], off offset:16
	v_lshrrev_b32_e32 v2, 2, v30
	v_and_b32_e32 v2, 60, v2
	v_lshrrev_b32_e32 v4, 2, v29
	v_and_b32_e32 v3, 15, v30
	v_and_b32_e32 v4, 60, v4
	v_add_u32_e32 v2, v36, v2
	v_lshl_add_u32 v3, v3, 2, v36
	v_add_u32_e32 v4, v36, v4
	v_and_b32_e32 v5, 15, v29
	v_lshrrev_b32_e32 v6, 2, v28
	v_lshrrev_b32_e32 v10, 2, v27
	ds_read_b32 v2, v2
	ds_read_b32 v3, v3 offset:64
	ds_read_b32 v4, v4
	v_lshl_add_u32 v5, v5, 2, v36
	v_and_b32_e32 v6, 60, v6
	v_and_b32_e32 v7, 15, v28
	v_and_b32_e32 v10, 60, v10
	ds_read_b32 v5, v5 offset:64
	v_add_u32_e32 v6, v36, v6
	v_lshl_add_u32 v7, v7, 2, v36
	v_add_u32_e32 v10, v36, v10
	v_and_b32_e32 v11, 15, v27
	ds_read_b32 v6, v6
	ds_read_b32 v7, v7 offset:64
	ds_read_b32 v10, v10
	v_lshl_add_u32 v11, v11, 2, v36
	ds_read_b32 v11, v11 offset:64
	s_waitcnt lgkmcnt(6)
	v_and_b32_e32 v27, 0x7f, v3
	s_waitcnt lgkmcnt(5)
	v_lshlrev_b32_e32 v3, 7, v4
	s_waitcnt lgkmcnt(4)
	v_and_b32_e32 v5, 0x7f, v5
	v_and_b32_e32 v3, 0x3f80, v3
	v_lshlrev_b32_e32 v2, 7, v2
	v_or_b32_e32 v3, v3, v5
	s_waitcnt lgkmcnt(1)
	v_lshlrev_b32_e32 v5, 7, v10
	v_lshlrev_b32_e32 v6, 7, v6
	v_and_b32_e32 v2, 0x3f80, v2
	s_waitcnt lgkmcnt(0)
	v_and_b32_e32 v4, 0x7f, v11
	v_and_b32_e32 v7, 0x7f, v7
	v_and_b32_e32 v5, 0x3f80, v5
	v_and_b32_e32 v6, 0x3f80, v6
	v_or_b32_e32 v2, v2, v27
	v_or_b32_e32 v5, v5, v4
	v_or_b32_e32 v4, v6, v7
	global_store_dwordx4 v[22:23], v[2:5], off offset:32
	v_lshrrev_b32_e32 v6, 2, v24
	v_and_b32_e32 v6, 60, v6
	v_pk_mul_f32 v[4:5], v[14:15], v[18:19] op_sel_hi:[1,0]
	v_pk_mul_f32 v[2:3], v[8:9], v[18:19] op_sel_hi:[1,0]
	global_store_dwordx4 v[20:21], v[2:5], off offset:32
	v_lshrrev_b32_e32 v8, 2, v19
	v_and_b32_e32 v7, 15, v24
	v_lshrrev_b32_e32 v2, 2, v26
	v_lshrrev_b32_e32 v4, 2, v25
	v_and_b32_e32 v2, 60, v2
	v_and_b32_e32 v3, 15, v26
	v_and_b32_e32 v4, 60, v4
	v_add_u32_e32 v2, v36, v2
	v_lshl_add_u32 v3, v3, 2, v36
	v_add_u32_e32 v4, v36, v4
	v_and_b32_e32 v5, 15, v25
	ds_read_b32 v2, v2
	ds_read_b32 v3, v3 offset:64
	ds_read_b32 v4, v4
	v_lshl_add_u32 v5, v5, 2, v36
	v_and_b32_e32 v8, 60, v8
	ds_read_b32 v5, v5 offset:64
	v_add_u32_e32 v6, v36, v6
	v_lshl_add_u32 v7, v7, 2, v36
	v_add_u32_e32 v8, v36, v8
	v_and_b32_e32 v9, 15, v19
	ds_read_b32 v6, v6
	ds_read_b32 v7, v7 offset:64
	ds_read_b32 v8, v8
	v_lshl_add_u32 v9, v9, 2, v36
	ds_read_b32 v9, v9 offset:64
	s_waitcnt lgkmcnt(6)
	v_and_b32_e32 v10, 0x7f, v3
	s_waitcnt lgkmcnt(5)
	v_lshlrev_b32_e32 v3, 7, v4
	s_waitcnt lgkmcnt(4)
	v_and_b32_e32 v5, 0x7f, v5
	v_and_b32_e32 v3, 0x3f80, v3
	v_lshlrev_b32_e32 v2, 7, v2
	v_or_b32_e32 v3, v3, v5
	s_waitcnt lgkmcnt(1)
	v_lshlrev_b32_e32 v5, 7, v8
	v_lshlrev_b32_e32 v6, 7, v6
	v_and_b32_e32 v2, 0x3f80, v2
	s_waitcnt lgkmcnt(0)
	v_and_b32_e32 v4, 0x7f, v9
	v_and_b32_e32 v7, 0x7f, v7
	v_and_b32_e32 v5, 0x3f80, v5
	v_and_b32_e32 v6, 0x3f80, v6
	v_or_b32_e32 v2, v2, v10
	v_or_b32_e32 v5, v5, v4
	v_or_b32_e32 v4, v6, v7
	global_store_dwordx4 v[22:23], v[2:5], off offset:48
	global_store_dwordx4 v[20:21], v[38:41], off
	global_store_dwordx4 v[22:23], v[32:35], off offset:16
	v_pk_mul_f32 v[4:5], v[16:17], v[18:19] op_sel_hi:[1,0]
	v_pk_mul_f32 v[2:3], v[12:13], v[18:19] op_sel_hi:[1,0]
	global_store_dwordx4 v[20:21], v[2:5], off offset:48
	s_branch .LBB0_21
